# post-GLA seams use the XCD-group barrier; the weight-conversion side job of workgroups>=128 is published separately (L2 write-back + per-workgroup count that every workgroup polls alongside the group
# speedup vs baseline: 1.0107x; 1.0101x over previous
; __device__ __forceinline__ unsigned xb_ld(unsigned* p)              { return __hip_atomic_load(p, __ATOMIC_RELAXED, __HIP_MEMORY_SCOPE_AGENT); }
; __device__ __forceinline__ unsigned xb_add(unsigned* p, unsigned v) { return __hip_atomic_fetch_add(p, v, __ATOMIC_RELAXED, __HIP_MEMORY_SCOPE_AGENT); }
; #define XB_SPIN(cond, bar) do { unsigned _sp = 0; while (cond) { __builtin_amdgcn_s_sleep(1); \
;     if ((++_sp & 255u) == 0u) { if (xb_ld(&(bar)[XB_TMO])) break; if (_sp > XB_SPIN_CAP) { atomicAdd(&(bar)[XB_TMO], 1u); break; } } } } while (0)
; #define PH_END   if (pid + 1 < hi) xcd_barrier(bar); } ++pid;
; __device__ __forceinline__ void xcd_barrier(const XcdBarrier& b) {
;     asm volatile("s_waitcnt vmcnt(0)" ::: "memory");
;     __syncthreads();
;     if (threadIdx.x == 0) {
;         unsigned* bar = b.bar;
;         __builtin_amdgcn_s_waitcnt(0);
;         unsigned nloc = b.st[0], nx = b.st[1];
;         if (nloc == 0u) { xcd_barrier_complete(bar, b.x, nloc, nx); b.st[0] = nloc; b.st[1] = nx; }
;         const unsigned old = xb_add(&bar[XB_XSUB(b.x)], 1u);
;         const unsigned gen = old / nloc;
;         if (old + 1u == (gen + 1u) * nloc) {
;             __builtin_amdgcn_fence(__ATOMIC_RELEASE, "agent");
;             asm volatile("s_waitcnt vmcnt(0)" ::: "memory");
;             const unsigned og = xb_add(&bar[XB_TOP], 1u);
;             const unsigned tg = og / nx;
;             if (og + 1u == (tg + 1u) * nx) xb_add(&bar[XB_TOPGEN], 1u);
;             else XB_SPIN(xb_ld(&bar[XB_TOPGEN]) == tg, bar);
;             __builtin_amdgcn_fence(__ATOMIC_ACQUIRE, "agent");
;             xb_add(&bar[XB_XGEN(b.x)], 1u);
;             asm volatile("s_waitcnt vmcnt(0)" ::: "memory");
;         } else {
;             XB_SPIN(xb_ld(&bar[XB_XGEN(b.x)]) == gen, bar);
;             __builtin_amdgcn_fence(__ATOMIC_ACQUIRE, "agent");
;             asm volatile("s_waitcnt vmcnt(0)" ::: "memory");
;         }
;     }
;     __syncthreads();
; }
; __global__ void __launch_bounds__(NTHREADS, 2) fwd_kernel(Args a) {
;     ...
; if ((i == 0 || i == 3) && G >= 256 && wg >= 128) { for (int rep = 0; rep < REP_CONV; ++rep) p0_phase(a, lds, G - 128, wg - 128, i == 0 ? 1 : 2, true); }
;             else for (int rep = 0; rep < REP_GLA; ++rep) gla_phase(lds, BIG, a.in[6] + j * 128, O2, G, wg);
;  PH_END
.LBB0_1523:
	s_waitcnt vmcnt(0)
	s_waitcnt lgkmcnt(0)
	s_barrier
	s_mov_b64 s[0:1], exec
	v_readlane_b32 s8, v252, 32
	v_readlane_b32 s9, v252, 33
	s_and_b64 s[8:9], s[0:1], s[8:9]
	s_mov_b64 exec, s[8:9]
	s_cbranch_execz .LBB0_1609
	v_mov_b32_e32 v0, 0x23fc8
	ds_read_b32 v1, v0
	s_waitcnt lgkmcnt(0)
	v_readfirstlane_b32 s40, v1
	s_cmp_eq_u32 s40, 1
	s_cbranch_scc0 .Lgb_orig_gla
	s_add_u32 s38, s24, 0x313600
	s_addc_u32 s39, s25, 0
	v_mov_b32_e32 v4, 0
	v_mov_b32_e32 v1, 1
	s_cmp_lt_u32 s2, 0x80
	s_cbranch_scc1 .Lgb_nopub_gla
	buffer_wbl2 sc1
	s_waitcnt vmcnt(0)
	global_atomic_add v4, v1, s[38:39]
.Lgb_nopub_gla:
	s_and_b32 s40, s2, 7
	s_lshl_b32 s40, s40, 7
	s_addk_i32 s40, 0x200
	v_mov_b32_e32 v0, s40
	global_atomic_add v2, v0, v1, s[38:39] sc0
	v_mov_b32_e32 v3, 0x23fd0
	ds_read_b32 v5, v3
	s_mov_b32 s40, 0
	s_waitcnt vmcnt(0) lgkmcnt(0)
	buffer_inv sc1
	v_add_u32_e32 v5, 0x80, v5
	ds_write_b32 v3, v5
	v_or_b32_e32 v2, 31, v2
	v_add_u32_e32 v2, 1, v2
.Lgb_spin_gla:
	global_load_dword v3, v0, s[38:39] sc1
	global_load_dword v1, v4, s[38:39] sc1
	s_waitcnt vmcnt(0)
	v_sub_u32_e32 v3, v3, v2
	v_sub_u32_e32 v1, v1, v5
	v_or_b32_e32 v3, v3, v1
	v_cmp_gt_i32_e32 vcc, 0, v3
	s_cbranch_vccz .Lgb_done_gla
	s_sleep 1
	s_add_i32 s40, s40, 1
	s_cmp_lt_u32 s40, 0x100000
	s_cbranch_scc1 .Lgb_spin_gla
.Lgb_done_gla:
	s_waitcnt lgkmcnt(0)
	s_branch .LBB0_1609
